# v52 + diff loops: saddr-form K/V LDS-DMA with 32-bit offsets; K-fragment LDS addresses formed once per tile and reused via ds_read immediate offset
# speedup vs baseline: 1.0538x; 1.0191x over previous
; DI float bf2f(unsigned short h) { return __uint_as_float((unsigned)h << 16); }
; template <int DQK, int MODE, int LDQ, int LDK, int LDV> ...
;     ...
;     float l_reg = 0.f; f32x16 o[4];
; #pragma unroll
;     for (int d = 0; d < 4; ++d)
; #pragma unroll
;         for (int r = 0; r < 16; ++r) o[d][r] = 0.f;
;     int kgo[NKP], vgo[2];
; #pragma unroll
;     for (int i = 0; i < NKP; ++i) { const int L = (wid + 8 * i) * 64 + lane, row = L / CPR, slot = L % CPR, cc = (slot & ~7) | ((slot & 7) ^ ((row >> 1) & 7)); kgo[i] = row * LDK + cc * 8; }
; #pragma unroll
;     for (int i = 0; i < 2; ++i) { const int L = (2 * wid + i) * 64 + lane, st = L >> 5, w5 = L & 31, kk = (st >> 2) * 8 + (w5 >> 2), c = (st & 3) * 32 + (w5 & 3) * 8;
;         const int k = (kk & ~0xC) | ((kk & 4) << 1) | ((kk & 8) >> 1); vgo[i] = k * LDV + c; }
;     ...
;     ATT_DMA_K(0); ATT_DMA_K(1); ATT_DMA_V(0, 0); ATT_DMA_K(2); ATT_DMA_V(1, 1);
;     bf16x8 qr[ND0];
;     { const bf16_t* Qw = Qb + (size_t)(wid * 32 + r32) * LDQ + hi * 8;
; #pragma unroll
;       for (int d0 = 0; d0 < ND0; ++d0) qr[d0] = *(const bf16x8*)(Qw + d0 * 16);
;       if constexpr (MODE == 0) {
;           float ss = 0.f;
; #pragma unroll
;           for (int d0 = 0; d0 < ND0; ++d0)
; #pragma unroll
;               for (int j = 0; j < 8; ++j) { const float f = bf2f((unsigned short)qr[d0][j]); ss += f * f; }
;           ss = swap_sum(ss);
;           const float rstd = rsqrtf(ss * (1.f / DQK) + EPS) * C;
; #pragma unroll
;           for (int d0 = 0; d0 < ND0; ++d0) { const float* g = gq + d0 * 16 + hi * 8;
;               { float f[8]; _Pragma("unroll") for (int j = 0; j < 8; ++j) f[j] = bf2f((unsigned short)qr[d0][j]) * rstd * g[j];
;                 u32x4 w = {cvtpk(f[0], f[1]), cvtpk(f[2], f[3]), cvtpk(f[4], f[5]), cvtpk(f[6], f[7])}; qr[d0] = __builtin_bit_cast(bf16x8, w); asm volatile("" ::: "memory"); } }
;       } }
;     const int qlo = q0 + wid * 32, qpos = qlo + r32;
;     const int tL = MODE == 0 ? 0 : (qlo >= 191 ? (qlo - 127) >> 6 : 0), tR = MODE == 0 ? NT : min(NT, (qlo + 222) >> 6);
;     float fL = 1.f, fR = 1.f; if constexpr (MODE != 0) { fL = __builtin_amdgcn_exp2f(bt[0]); fR = __builtin_amdgcn_exp2f(-bt[448]); }
;     ...
;     const int vbase = (int)(unsigned)(size_t)lds + V_OFF + v_rd_base(lane);
.LBB0_1919:
	s_lshl_b32 s87, s86, 7
	s_and_b32 s54, s0, 0xffffffc0
	s_min_i32 s97, s58, 64
	s_and_b32 s92, s73, 0xf00
	s_cmp_gt_i32 s55, 0
	s_cselect_b64 s[4:5], -1, 0
	s_add_i32 s93, 0, 0x18000
	s_add_i32 s1, s92, s94
	s_add_u32 s90, s2, s84
	v_add_lshl_u32 v2, s1, v2, 2
	s_addc_u32 s91, s3, 0
	v_readlane_b32 s1, v255, 6
	s_add_u32 s2, s1, s90
	s_addc_u32 s3, s76, s91
	s_add_i32 s7, s7, s6
	v_lshl_add_u64 v[100:101], v[0:1], 1, s[2:3]
	v_subrev_u32_e32 v100, s34, v100
	v_add3_u32 v0, s7, v6, v4
	v_lshl_or_b32 v0, v0, 11, v3
	v_and_b32_e32 v7, 63, v7
	v_add_u32_e32 v0, v0, v5
	s_add_u32 s2, s77, s90
	v_exp_f32_e32 v112, v9
	v_lshlrev_b32_e32 v8, 3, v7
	v_lshlrev_b32_e32 v9, 4, v7
	v_lshlrev_b32_e32 v7, 1, v7
	v_ashrrev_i32_e32 v1, 31, v0
	s_addc_u32 s3, s78, s91
	v_exp_f32_e64 v113, -v10
	v_and_b32_e32 v7, 32, v7
	v_lshl_add_u64 v[102:103], v[0:1], 1, s[2:3]
	v_subrev_u32_e32 v102, s34, v102
	v_add_u32_e32 v0, 64, v0
	v_and_b32_e32 v9, 0xc0, v9
	v_and_or_b32 v7, v8, s66, v7
	v_sub_u32_e32 v2, v130, v2
	v_ashrrev_i32_e32 v1, 31, v0
	v_mov_b32_e32 v14, v131
	v_mov_b32_e32 v15, v131
	v_add3_u32 v106, v9, s93, v7
	v_add_u32_e32 v119, 0, v2
	v_lshl_add_u64 v[104:105], v[0:1], 1, s[2:3]
	v_subrev_u32_e32 v104, s34, v104
	v_mov_b32_e32 v0, v131
	v_mov_b32_e32 v1, v131
	v_mov_b32_e32 v2, v131
	v_mov_b32_e32 v3, v131
	v_mov_b32_e32 v4, v131
	v_mov_b32_e32 v5, v131
	v_mov_b32_e32 v6, v131
	v_mov_b32_e32 v7, v131
	v_mov_b32_e32 v8, v131
	v_mov_b32_e32 v9, v131
	v_mov_b32_e32 v10, v131
	v_mov_b32_e32 v11, v131
	v_mov_b32_e32 v12, v131
	v_mov_b32_e32 v13, v131
	v_mov_b64_e32 v[62:63], v[14:15]
	v_mov_b64_e32 v[46:47], v[14:15]
	v_mov_b64_e32 v[30:31], v[14:15]
	s_mov_b32 s0, 1
	s_mov_b32 s23, 0
	s_mov_b32 s96, 2
	s_sub_i32 s62, 0, s55
	s_sub_i32 s6, 0, s97
	v_mov_b32_e32 v120, 0
	s_movk_i32 s7, 0xc300
	s_movk_i32 s22, 0x6000
	v_mov_b32_e32 v196, v107
	v_mov_b32_e32 v197, v108
	v_mov_b32_e32 v198, v109
	v_mov_b32_e32 v199, v110
	v_mov_b64_e32 v[60:61], v[12:13]
	v_mov_b64_e32 v[58:59], v[10:11]
	v_mov_b64_e32 v[56:57], v[8:9]
	v_mov_b64_e32 v[54:55], v[6:7]
	v_mov_b64_e32 v[52:53], v[4:5]
	v_mov_b64_e32 v[50:51], v[2:3]
	v_mov_b64_e32 v[48:49], v[0:1]
	v_mov_b64_e32 v[44:45], v[12:13]
	v_mov_b64_e32 v[42:43], v[10:11]
	v_mov_b64_e32 v[40:41], v[8:9]
	v_mov_b64_e32 v[38:39], v[6:7]
	v_mov_b64_e32 v[36:37], v[4:5]
	v_mov_b64_e32 v[34:35], v[2:3]
	v_mov_b64_e32 v[32:33], v[0:1]
	v_mov_b64_e32 v[28:29], v[12:13]
	v_mov_b64_e32 v[26:27], v[10:11]
	v_mov_b64_e32 v[24:25], v[8:9]
	v_mov_b64_e32 v[22:23], v[6:7]
	v_mov_b64_e32 v[20:21], v[4:5]
	v_mov_b64_e32 v[18:19], v[2:3]
	v_mov_b64_e32 v[16:17], v[0:1]
	s_mov_b32 s64, 1
	s_cmp_lt_u32 s33, 0x100
	s_cbranch_scc1 .Lstg_d0_pre_9
	s_waitcnt vmcnt(3)
	s_barrier

; #define LAS __attribute__((address_space(3)))
; DI void expsum(f32x16& p, float& l_reg, bf16x8& pa0, bf16x8& pa1) {
; #pragma unroll
;     for (int r = 0; r < 16; ++r) p[r] = __builtin_amdgcn_exp2f(p[r]);
;     float ps = 0.f;
; #pragma unroll
;     for (int r = 0; r < 16; ++r) ps += p[r];
;     l_reg += ps; asm volatile("" : "+v"(l_reg));
;     ...
;     ATT_PK4(p, 0, pa0); ATT_PK4(p, 8, pa1);
;     ...
; }
; DI int v_rd_base(int lane) { return ((lane & 3) << 3) | (((lane >> 2) & 3) << 6) | (((lane >> 4) & 1) << 5) | (((lane >> 5) & 1) << 8); }
; template <int OFF> DI s16x4 tr_read(int vb) { s16x4 r; asm volatile("ds_read_b64_tr_b16 %0, %1 offset:%2" : "=&v"(r) : "v"(vb), "i"(OFF) : "memory"); return r; }
; template <int H> DI void v_reads(s16x4* vf, int vb) {
;     vf[0] = tr_read<v_rd_off(0, 2 * H, 0)>(vb); vf[1] = tr_read<v_rd_off(0, 2 * H, 1)>(vb); vf[2] = tr_read<v_rd_off(0, 2 * H + 1, 0)>(vb); vf[3] = tr_read<v_rd_off(0, 2 * H + 1, 1)>(vb);
;     vf[4] = tr_read<v_rd_off(1, 2 * H, 0)>(vb); vf[5] = tr_read<v_rd_off(1, 2 * H, 1)>(vb); vf[6] = tr_read<v_rd_off(1, 2 * H + 1, 0)>(vb); vf[7] = tr_read<v_rd_off(1, 2 * H + 1, 1)>(vb);
;     vf[8] = tr_read<v_rd_off(2, 2 * H, 0)>(vb); vf[9] = tr_read<v_rd_off(2, 2 * H, 1)>(vb); vf[10] = tr_read<v_rd_off(2, 2 * H + 1, 0)>(vb); vf[11] = tr_read<v_rd_off(2, 2 * H + 1, 1)>(vb);
;     vf[12] = tr_read<v_rd_off(3, 2 * H, 0)>(vb); vf[13] = tr_read<v_rd_off(3, 2 * H, 1)>(vb); vf[14] = tr_read<v_rd_off(3, 2 * H + 1, 0)>(vb); vf[15] = tr_read<v_rd_off(3, 2 * H + 1, 1)>(vb);
; }
; DI void pv_mma(f32x16* o, const s16x4* vf, bf16x8 pa0, bf16x8 pa1) {
;     ...
; #pragma unroll
;     for (int d0 = 0; d0 < 4; ++d0) {
;         o[d0] = __builtin_amdgcn_mfma_f32_32x32x16_bf16(pa0, ATT_PK(vf[4 * d0], vf[4 * d0 + 1]), o[d0], 0, 0, 0);
;         o[d0] = __builtin_amdgcn_mfma_f32_32x32x16_bf16(pa1, ATT_PK(vf[4 * d0 + 2], vf[4 * d0 + 3]), o[d0], 0, 0, 0); }
;     ...
; }
; template <int DQK, int D0A, int D0B> DI void k_reads(bf16x8* kf, const LAS unsigned char* Ks, int half, int r32, int hi) {
; #pragma unroll
;     for (int d0 = D0A; d0 < D0B; ++d0) kf[d0 - D0A] = *(const LAS bf16x8*)(Ks + half * (32 * DQK * 2) + kswz<DQK>(r32, (d0 * 16 + hi * 8) * 2));
; }
; template <int D0A, int D0B> DI void qk_mma(f32x16& p, const bf16x8* kf, const bf16x8* qr) {
; #pragma unroll
;     for (int d0 = D0A; d0 < D0B; ++d0) {
.Lstg_d0_top_10:
	s_setprio 0
	s_add_i32 s1, s95, s1
	global_load_lds_dwordx4 v100, s[34:35]
	s_add_i32 s2, s1, 0x400
	s_mov_b32 m0, s1
	s_add_i32 s1, s62, s0
	global_load_lds_dwordx4 v102, s[34:35]
	s_mov_b32 m0, s2
	s_add_i32 s74, s6, s0
	global_load_lds_dwordx4 v104, s[34:35]
	s_cmp_eq_u32 s1, 1
	s_cselect_b64 s[2:3], -1, 0
	s_and_b64 vcc, s[4:5], s[2:3]
	s_cmp_eq_u32 s74, 1
	s_cselect_b64 s[2:3], -1, 0
	s_or_b64 vcc, s[2:3], vcc
	s_andn2_b64 vcc, exec, vcc
	s_mov_b32 s1, s23
	s_cbranch_vccnz .LBB0_1922
	v_cndmask_b32_e64 v122, v112, v113, s[2:3]
	v_pk_mul_f32 v[14:15], v[14:15], v[122:123] op_sel_hi:[1,0]
	v_pk_mul_f32 v[12:13], v[12:13], v[122:123] op_sel_hi:[1,0]
	v_pk_mul_f32 v[10:11], v[10:11], v[122:123] op_sel_hi:[1,0]
	v_pk_mul_f32 v[8:9], v[8:9], v[122:123] op_sel_hi:[1,0]
	v_pk_mul_f32 v[6:7], v[6:7], v[122:123] op_sel_hi:[1,0]
	v_pk_mul_f32 v[4:5], v[4:5], v[122:123] op_sel_hi:[1,0]
	v_pk_mul_f32 v[2:3], v[2:3], v[122:123] op_sel_hi:[1,0]
	v_pk_mul_f32 v[0:1], v[0:1], v[122:123] op_sel_hi:[1,0]
	v_pk_mul_f32 v[62:63], v[62:63], v[122:123] op_sel_hi:[1,0]
	v_pk_mul_f32 v[60:61], v[60:61], v[122:123] op_sel_hi:[1,0]
	v_pk_mul_f32 v[58:59], v[58:59], v[122:123] op_sel_hi:[1,0]
	v_pk_mul_f32 v[56:57], v[56:57], v[122:123] op_sel_hi:[1,0]
	v_pk_mul_f32 v[54:55], v[54:55], v[122:123] op_sel_hi:[1,0]
	v_pk_mul_f32 v[52:53], v[52:53], v[122:123] op_sel_hi:[1,0]
	v_pk_mul_f32 v[50:51], v[50:51], v[122:123] op_sel_hi:[1,0]
	v_pk_mul_f32 v[48:49], v[48:49], v[122:123] op_sel_hi:[1,0]
	v_pk_mul_f32 v[46:47], v[46:47], v[122:123] op_sel_hi:[1,0]
	v_pk_mul_f32 v[44:45], v[44:45], v[122:123] op_sel_hi:[1,0]
	v_pk_mul_f32 v[42:43], v[42:43], v[122:123] op_sel_hi:[1,0]
	v_pk_mul_f32 v[40:41], v[40:41], v[122:123] op_sel_hi:[1,0]
	v_pk_mul_f32 v[38:39], v[38:39], v[122:123] op_sel_hi:[1,0]
	v_pk_mul_f32 v[36:37], v[36:37], v[122:123] op_sel_hi:[1,0]
	v_pk_mul_f32 v[34:35], v[34:35], v[122:123] op_sel_hi:[1,0]
	v_pk_mul_f32 v[32:33], v[32:33], v[122:123] op_sel_hi:[1,0]
	v_pk_mul_f32 v[30:31], v[30:31], v[122:123] op_sel_hi:[1,0]
	v_pk_mul_f32 v[28:29], v[28:29], v[122:123] op_sel_hi:[1,0]
	v_pk_mul_f32 v[26:27], v[26:27], v[122:123] op_sel_hi:[1,0]
	v_pk_mul_f32 v[24:25], v[24:25], v[122:123] op_sel_hi:[1,0]
	v_pk_mul_f32 v[22:23], v[22:23], v[122:123] op_sel_hi:[1,0]
	v_pk_mul_f32 v[20:21], v[20:21], v[122:123] op_sel_hi:[1,0]
	v_pk_mul_f32 v[18:19], v[18:19], v[122:123] op_sel_hi:[1,0]
	v_pk_mul_f32 v[16:17], v[16:17], v[122:123] op_sel_hi:[1,0]
	v_mul_f32_e32 v120, v120, v122
.LBB0_1922:
	s_add_i32 s3, s0, -1
	ds_read_b128 v[122:125], v196 offset:4096
	ds_read_b128 v[132:135], v197 offset:4096
	s_lshl_b32 s2, s1, 14
	ds_read_b128 v[136:139], v198 offset:4096
	ds_read_b128 v[140:143], v199 offset:4096
	v_add_u32_e32 v121, s2, v106
	ds_read_b64_tr_b16 v[144:145], v121 offset:0
	ds_read_b64_tr_b16 v[146:147], v121 offset:0x800
	ds_read_b64_tr_b16 v[148:149], v121 offset:0x1000
	ds_read_b64_tr_b16 v[150:151], v121 offset:0x1800
	ds_read_b64_tr_b16 v[152:153], v121 offset:0x200
	ds_read_b64_tr_b16 v[154:155], v121 offset:0xa00
	ds_read_b64_tr_b16 v[156:157], v121 offset:0x1200
	ds_read_b64_tr_b16 v[158:159], v121 offset:0x1a00
	ds_read_b64_tr_b16 v[162:163], v121 offset:0x400
	ds_read_b64_tr_b16 v[164:165], v121 offset:0xc00
	ds_read_b64_tr_b16 v[166:167], v121 offset:0x1400
	ds_read_b64_tr_b16 v[168:169], v121 offset:0x1c00
	ds_read_b64_tr_b16 v[170:171], v121 offset:0x600
	ds_read_b64_tr_b16 v[172:173], v121 offset:0xe00
	ds_read_b64_tr_b16 v[174:175], v121 offset:0x1600
	ds_read_b64_tr_b16 v[176:177], v121 offset:0x1e00
	s_setprio 2
	v_exp_f32_e32 v64, v64
	v_exp_f32_e32 v65, v65
	v_exp_f32_e32 v66, v66
	v_exp_f32_e32 v67, v67
	v_exp_f32_e32 v68, v68
	v_exp_f32_e32 v69, v69
	v_add_f32_e32 v126, v65, v64
	v_exp_f32_e32 v70, v70
	v_add_f32_e32 v126, v66, v126
	v_exp_f32_e32 v71, v71
	v_add_f32_e32 v126, v67, v126
	v_exp_f32_e32 v72, v72
	v_add_f32_e32 v126, v68, v126
	v_exp_f32_e32 v73, v73
	v_add_f32_e32 v126, v69, v126
	v_exp_f32_e32 v74, v74
	v_add_f32_e32 v126, v70, v126
	v_exp_f32_e32 v75, v75
	v_add_f32_e32 v126, v71, v126
	v_exp_f32_e32 v76, v76
	v_add_f32_e32 v126, v72, v126
	v_exp_f32_e32 v77, v77
	v_add_f32_e32 v126, v73, v126
	v_exp_f32_e32 v78, v78
	v_add_f32_e32 v126, v74, v126
	v_exp_f32_e32 v79, v79
	v_add_f32_e32 v126, v75, v126
	v_add_f32_e32 v126, v76, v126
	v_add_f32_e32 v126, v77, v126
	v_add_f32_e32 v126, v78, v126
	v_add_f32_e32 v126, v79, v126
	v_add_f32_e32 v120, v126, v120
	v_cvt_pk_bf16_f32 v64, v64, v65
	v_cvt_pk_bf16_f32 v65, v66, v67
	v_cvt_pk_bf16_f32 v66, v68, v69
	v_cvt_pk_bf16_f32 v67, v70, v71
	v_cvt_pk_bf16_f32 v68, v72, v73
	v_cvt_pk_bf16_f32 v69, v74, v75
	v_cvt_pk_bf16_f32 v70, v76, v77
	v_cvt_pk_bf16_f32 v71, v78, v79
	s_nop 0
	v_permlane32_swap_b32_e32 v64, v66
	v_permlane32_swap_b32_e32 v65, v67
	v_permlane32_swap_b32_e32 v68, v70
	v_permlane32_swap_b32_e32 v69, v71
	s_waitcnt lgkmcnt(0)
	s_setprio 1
	v_mfma_f32_32x32x16_bf16 v[0:15], v[64:67], v[144:147], v[0:15]
	s_cmp_lt_i32 s3, s55
	s_cselect_b64 vcc, -1, 0
	s_cmp_ge_i32 s3, s97
	s_cselect_b64 s[74:75], -1, 0
	s_or_b64 s[74:75], vcc, s[74:75]
	s_and_b64 vcc, exec, s[74:75]
	v_mfma_f32_32x32x16_bf16 v[48:63], v[64:67], v[152:155], v[48:63]
	v_mfma_f32_32x32x16_bf16 v[32:47], v[64:67], v[162:165], v[32:47]
	v_mfma_f32_32x32x16_bf16 v[16:31], v[64:67], v[170:173], v[16:31]
	v_mfma_f32_32x32x16_bf16 v[0:15], v[68:71], v[148:151], v[0:15]
	v_mfma_f32_32x32x16_bf16 v[48:63], v[68:71], v[156:159], v[48:63]
	v_mfma_f32_32x32x16_bf16 v[32:47], v[68:71], v[166:169], v[32:47]
	v_mfma_f32_32x32x16_bf16 v[16:31], v[68:71], v[174:177], v[16:31]
	v_mfma_f32_32x32x16_bf16 v[64:79], v[122:125], v[92:95], 0
	v_mfma_f32_32x32x16_bf16 v[64:79], v[132:135], v[88:91], v[64:79]
	v_mfma_f32_32x32x16_bf16 v[64:79], v[136:139], v[84:87], v[64:79]
	v_mfma_f32_32x32x16_bf16 v[64:79], v[140:143], v[80:83], v[64:79]
	s_setprio 0
	v_add_u32_e32 v122, s7, v119
	s_cbranch_vccnz .LBB0_1924
	v_add_u32_e32 v138, 0x28908, v122
	v_add_u32_e32 v140, 0x28920, v122
	v_add_u32_e32 v142, 0x28928, v122
	v_add_u32_e32 v124, 0x28940, v122
	v_add_u32_e32 v126, 0x28948, v122
	v_add_u32_e32 v132, 0x28960, v122
	v_add_u32_e32 v134, 0x28968, v122
	v_add_u32_e32 v123, 0x28900, v122
	ds_read2_b32 v[124:125], v124 offset1:1
	ds_read2_b32 v[126:127], v126 offset1:1
	ds_read2_b32 v[132:133], v132 offset1:1
	ds_read2_b32 v[134:135], v134 offset1:1
	ds_read2_b32 v[136:137], v123 offset1:1
	ds_read2_b32 v[138:139], v138 offset1:1
	ds_read2_b32 v[140:141], v140 offset1:1
	ds_read2_b32 v[142:143], v142 offset1:1
	s_waitcnt lgkmcnt(0)
	v_pk_add_f32 v[78:79], v[78:79], v[134:135]
	v_pk_add_f32 v[76:77], v[76:77], v[132:133]
	v_pk_add_f32 v[74:75], v[74:75], v[126:127]
	v_pk_add_f32 v[72:73], v[72:73], v[124:125]
	v_pk_add_f32 v[70:71], v[70:71], v[142:143]
	v_pk_add_f32 v[68:69], v[68:69], v[140:141]
	v_pk_add_f32 v[66:67], v[66:67], v[138:139]
	v_pk_add_f32 v[64:65], v[64:65], v[136:137]
; #define LAS __attribute__((address_space(3)))
; DI void expsum(f32x16& p, float& l_reg, bf16x8& pa0, bf16x8& pa1) {
; #pragma unroll
;     for (int r = 0; r < 16; ++r) p[r] = __builtin_amdgcn_exp2f(p[r]);
;     float ps = 0.f;
; #pragma unroll
;     for (int r = 0; r < 16; ++r) ps += p[r];
;     l_reg += ps; asm volatile("" : "+v"(l_reg));
;     ...
;     ATT_PK4(p, 0, pa0); ATT_PK4(p, 8, pa1);
;     ...
; }
; DI int v_rd_base(int lane) { return ((lane & 3) << 3) | (((lane >> 2) & 3) << 6) | (((lane >> 4) & 1) << 5) | (((lane >> 5) & 1) << 8); }
; template <int OFF> DI s16x4 tr_read(int vb) { s16x4 r; asm volatile("ds_read_b64_tr_b16 %0, %1 offset:%2" : "=&v"(r) : "v"(vb), "i"(OFF) : "memory"); return r; }
; template <int H> DI void v_reads(s16x4* vf, int vb) {
;     vf[0] = tr_read<v_rd_off(0, 2 * H, 0)>(vb); vf[1] = tr_read<v_rd_off(0, 2 * H, 1)>(vb); vf[2] = tr_read<v_rd_off(0, 2 * H + 1, 0)>(vb); vf[3] = tr_read<v_rd_off(0, 2 * H + 1, 1)>(vb);
;     vf[4] = tr_read<v_rd_off(1, 2 * H, 0)>(vb); vf[5] = tr_read<v_rd_off(1, 2 * H, 1)>(vb); vf[6] = tr_read<v_rd_off(1, 2 * H + 1, 0)>(vb); vf[7] = tr_read<v_rd_off(1, 2 * H + 1, 1)>(vb);
;     vf[8] = tr_read<v_rd_off(2, 2 * H, 0)>(vb); vf[9] = tr_read<v_rd_off(2, 2 * H, 1)>(vb); vf[10] = tr_read<v_rd_off(2, 2 * H + 1, 0)>(vb); vf[11] = tr_read<v_rd_off(2, 2 * H + 1, 1)>(vb);
;     vf[12] = tr_read<v_rd_off(3, 2 * H, 0)>(vb); vf[13] = tr_read<v_rd_off(3, 2 * H, 1)>(vb); vf[14] = tr_read<v_rd_off(3, 2 * H + 1, 0)>(vb); vf[15] = tr_read<v_rd_off(3, 2 * H + 1, 1)>(vb);
; }
; DI void pv_mma(f32x16* o, const s16x4* vf, bf16x8 pa0, bf16x8 pa1) {
;     ...
; #pragma unroll
;     for (int d0 = 0; d0 < 4; ++d0) {
;         o[d0] = __builtin_amdgcn_mfma_f32_32x32x16_bf16(pa0, ATT_PK(vf[4 * d0], vf[4 * d0 + 1]), o[d0], 0, 0, 0);
;         o[d0] = __builtin_amdgcn_mfma_f32_32x32x16_bf16(pa1, ATT_PK(vf[4 * d0 + 2], vf[4 * d0 + 3]), o[d0], 0, 0, 0); }
;     ...
; }
; template <int DQK, int D0A, int D0B> DI void k_reads(bf16x8* kf, const LAS unsigned char* Ks, int half, int r32, int hi) {
; #pragma unroll
;     for (int d0 = D0A; d0 < D0B; ++d0) kf[d0 - D0A] = *(const LAS bf16x8*)(Ks + half * (32 * DQK * 2) + kswz<DQK>(r32, (d0 * 16 + hi * 8) * 2));
; }
; template <int D0A, int D0B> DI void qk_mma(f32x16& p, const bf16x8* kf, const bf16x8* qr) {
; #pragma unroll
;     for (int d0 = D0A; d0 < D0B; ++d0) {
.LBB0_1924:
	s_add_i32 s3, s22, 0xffffc000
	s_and_b32 s3, s3, 0x6000
	v_add_u32_e32 v196, s3, v107
	v_add_u32_e32 v197, s3, v108
	v_add_u32_e32 v198, s3, v109
	v_add_u32_e32 v199, s3, v110
	ds_read_b128 v[124:127], v196
	ds_read_b128 v[132:135], v197
	ds_read_b128 v[136:139], v198
	ds_read_b128 v[140:143], v199
	ds_read_b64_tr_b16 v[144:145], v121 offset:0x2000
	ds_read_b64_tr_b16 v[146:147], v121 offset:0x2800
	ds_read_b64_tr_b16 v[148:149], v121 offset:0x3000
	ds_read_b64_tr_b16 v[150:151], v121 offset:0x3800
	ds_read_b64_tr_b16 v[152:153], v121 offset:0x2200
	ds_read_b64_tr_b16 v[154:155], v121 offset:0x2a00
	ds_read_b64_tr_b16 v[156:157], v121 offset:0x3200
	ds_read_b64_tr_b16 v[158:159], v121 offset:0x3a00
	ds_read_b64_tr_b16 v[162:163], v121 offset:0x2400
	ds_read_b64_tr_b16 v[164:165], v121 offset:0x2c00
	ds_read_b64_tr_b16 v[166:167], v121 offset:0x3400
	ds_read_b64_tr_b16 v[168:169], v121 offset:0x3c00
	ds_read_b64_tr_b16 v[170:171], v121 offset:0x2600
	ds_read_b64_tr_b16 v[172:173], v121 offset:0x2e00
	ds_read_b64_tr_b16 v[174:175], v121 offset:0x3600
	ds_read_b64_tr_b16 v[176:177], v121 offset:0x3e00
	s_setprio 2
	v_exp_f32_e32 v64, v64
	v_exp_f32_e32 v65, v65
	v_exp_f32_e32 v66, v66
	v_exp_f32_e32 v67, v67
	v_exp_f32_e32 v68, v68
	v_exp_f32_e32 v69, v69
	v_add_f32_e32 v121, v65, v64
	v_exp_f32_e32 v70, v70
	v_add_f32_e32 v121, v66, v121
	v_exp_f32_e32 v71, v71
	v_add_f32_e32 v121, v67, v121
	v_exp_f32_e32 v72, v72
	v_add_f32_e32 v121, v68, v121
	v_exp_f32_e32 v73, v73
	v_add_f32_e32 v121, v69, v121
	v_exp_f32_e32 v74, v74
	v_add_f32_e32 v121, v70, v121
	v_exp_f32_e32 v75, v75
	v_add_f32_e32 v121, v71, v121
	v_exp_f32_e32 v76, v76
	v_add_f32_e32 v121, v72, v121
	v_exp_f32_e32 v77, v77
	v_add_f32_e32 v121, v73, v121
	v_exp_f32_e32 v78, v78
	v_add_f32_e32 v121, v74, v121
	v_exp_f32_e32 v79, v79
	v_add_f32_e32 v121, v75, v121
	v_add_f32_e32 v121, v76, v121
	v_add_f32_e32 v121, v77, v121
	v_add_f32_e32 v121, v78, v121
	v_add_f32_e32 v121, v79, v121
	v_add_f32_e32 v120, v120, v121
	v_cvt_pk_bf16_f32 v64, v64, v65
	v_cvt_pk_bf16_f32 v65, v66, v67
	v_cvt_pk_bf16_f32 v66, v68, v69
	v_cvt_pk_bf16_f32 v67, v70, v71
	v_cvt_pk_bf16_f32 v68, v72, v73
	v_cvt_pk_bf16_f32 v69, v74, v75
	v_cvt_pk_bf16_f32 v70, v76, v77
	v_cvt_pk_bf16_f32 v71, v78, v79
	s_nop 0
	v_permlane32_swap_b32_e32 v64, v66
	v_permlane32_swap_b32_e32 v65, v67
	v_permlane32_swap_b32_e32 v68, v70
	v_permlane32_swap_b32_e32 v69, v71
	s_waitcnt lgkmcnt(0)
	s_setprio 1
	s_cmp_lt_u32 s33, 0x100
	s_cbranch_scc1 .Lstg_d0_mid_11
	s_waitcnt vmcnt(3)
	s_barrier

; #define SBAR() __builtin_amdgcn_sched_barrier(0)
; #define ATT_DMA_K(t) do { const bf16_t* kg_ = Kh + (size_t)(t) * 64 * LDK; LAS unsigned char* sb_ = lds + ((t) & 3) * KBUF; \
;     _Pragma("unroll") for (int i_ = 0; i_ < NKP; ++i_) __builtin_amdgcn_global_load_lds((const unsigned*)(kg_ + kgo[i_]), (LAS unsigned*)(sb_ + (wid + 8 * i_) * 1024), 16, 0, 0); } while (0)
; #define ATT_DMA_V(t, vs) do { const bf16_t* vg_ = Vh + (size_t)(t) * 64 * LDV; LAS unsigned char* sb_ = lds + V_OFF + (vs) * SHM_V; \
;     _Pragma("unroll") for (int i_ = 0; i_ < 2; ++i_) __builtin_amdgcn_global_load_lds((const unsigned*)(vg_ + vgo[i_]), (LAS unsigned*)(sb_ + (2 * wid + i_) * 1024), 16, 0, 0); } while (0)
; #define ATT_SEG(t) do { if constexpr (MODE != 0) { if (((t) == tL && tL > 0) || (t) == tR) { const float f_ = (t) == tR ? fR : fL; l_reg *= f_; \
;     _Pragma("unroll") for (int d = 0; d < 4; ++d) _Pragma("unroll") for (int r = 0; r < 16; ++r) o[d][r] *= f_; } } } while (0)
; #define ATT_TOP(N) do { asm volatile("s_waitcnt vmcnt(%0)" :: "n"(N) : "memory"); __builtin_amdgcn_s_barrier(); asm volatile("" ::: "memory"); } while (0)
; template <int DQK, int MODE, int LDQ, int LDK, int LDV> ...
;     ...
;     for (int j = 0; j < NT; ++j) {
;         if (j + 2 < NT) ATT_TOP(NKP + 2); else ATT_TOP(0);
;         if (j + 3 < NT) ATT_DMA_K(j + 3);
;         if (j + 2 < NT) ATT_DMA_V(j + 2, v2);
;         ATT_SEG(j); SBAR();
;         ATT_STEP(pA, pB, 0, v0, true, 1, j);
;         ATT_STEP(pB, pA, 1, v0, (j + 1 < NT), 0, j + 1);
;         { const int t_ = v0; v0 = v1; v1 = v2; v2 = t_; }
;     }
.LBB0_1926:
	s_addk_i32 s7, 0x100
	s_addk_i32 s22, 0x2000
	s_add_i32 s0, s0, 1
	v_add_u32_e32 v100, s8, v100
	v_add_u32_e32 v102, s8, v102
	s_cmp_eq_u32 s7, 0
	v_add_u32_e32 v104, s8, v104
	s_cbranch_scc1 .LBB0_1928
	s_mov_b32 s23, s64
	s_mov_b32 s64, s96
	s_mov_b32 s96, s1
	s_branch .LBB0_1920

; DI float bf2f(unsigned short h) { return __uint_as_float((unsigned)h << 16); }
; template <int DQK, int MODE, int LDQ, int LDK, int LDV> ...
;     ...
;     float l_reg = 0.f; f32x16 o[4];
; #pragma unroll
;     for (int d = 0; d < 4; ++d)
; #pragma unroll
;         for (int r = 0; r < 16; ++r) o[d][r] = 0.f;
;     int kgo[NKP], vgo[2];
; #pragma unroll
;     for (int i = 0; i < NKP; ++i) { const int L = (wid + 8 * i) * 64 + lane, row = L / CPR, slot = L % CPR, cc = (slot & ~7) | ((slot & 7) ^ ((row >> 1) & 7)); kgo[i] = row * LDK + cc * 8; }
; #pragma unroll
;     for (int i = 0; i < 2; ++i) { const int L = (2 * wid + i) * 64 + lane, st = L >> 5, w5 = L & 31, kk = (st >> 2) * 8 + (w5 >> 2), c = (st & 3) * 32 + (w5 & 3) * 8;
;         const int k = (kk & ~0xC) | ((kk & 4) << 1) | ((kk & 8) >> 1); vgo[i] = k * LDV + c; }
;     ...
;     ATT_DMA_K(0); ATT_DMA_K(1); ATT_DMA_V(0, 0); ATT_DMA_K(2); ATT_DMA_V(1, 1);
;     bf16x8 qr[ND0];
;     { const bf16_t* Qw = Qb + (size_t)(wid * 32 + r32) * LDQ + hi * 8;
; #pragma unroll
;       for (int d0 = 0; d0 < ND0; ++d0) qr[d0] = *(const bf16x8*)(Qw + d0 * 16);
;       if constexpr (MODE == 0) {
;           float ss = 0.f;
; #pragma unroll
;           for (int d0 = 0; d0 < ND0; ++d0)
; #pragma unroll
;               for (int j = 0; j < 8; ++j) { const float f = bf2f((unsigned short)qr[d0][j]); ss += f * f; }
;           ss = swap_sum(ss);
;           const float rstd = rsqrtf(ss * (1.f / DQK) + EPS) * C;
; #pragma unroll
;           for (int d0 = 0; d0 < ND0; ++d0) { const float* g = gq + d0 * 16 + hi * 8;
;               { float f[8]; _Pragma("unroll") for (int j = 0; j < 8; ++j) f[j] = bf2f((unsigned short)qr[d0][j]) * rstd * g[j];
;                 u32x4 w = {cvtpk(f[0], f[1]), cvtpk(f[2], f[3]), cvtpk(f[4], f[5]), cvtpk(f[6], f[7])}; qr[d0] = __builtin_bit_cast(bf16x8, w); asm volatile("" ::: "memory"); } }
;       } }
;     const int qlo = q0 + wid * 32, qpos = qlo + r32;
;     const int tL = MODE == 0 ? 0 : (qlo >= 191 ? (qlo - 127) >> 6 : 0), tR = MODE == 0 ? NT : min(NT, (qlo + 222) >> 6);
;     float fL = 1.f, fR = 1.f; if constexpr (MODE != 0) { fL = __builtin_amdgcn_exp2f(bt[0]); fR = __builtin_amdgcn_exp2f(-bt[448]); }
;     ...
;     const int vbase = (int)(unsigned)(size_t)lds + V_OFF + v_rd_base(lane);
.LBB0_1950:
	s_and_b32 s44, s0, 0xffffffc0
	s_min_i32 s52, s45, 64
	s_cmp_gt_i32 s47, 0
	s_cselect_b64 s[4:5], -1, 0
	s_add_i32 s92, s92, s46
	s_add_u32 s6, s79, s90
	s_addc_u32 s7, s80, s91
	s_add_i32 s3, s3, s2
	v_lshl_add_u64 v[100:101], v[0:1], 1, s[6:7]
	v_subrev_u32_e32 v100, s34, v100
	v_add3_u32 v0, s3, v6, v4
	v_lshl_or_b32 v0, v0, 11, v3
	v_and_b32_e32 v7, 63, v7
	v_add_u32_e32 v0, v0, v5
	s_add_u32 s2, s77, s90
	v_exp_f32_e32 v112, v9
	v_lshlrev_b32_e32 v8, 3, v7
	v_lshlrev_b32_e32 v9, 4, v7
	v_lshlrev_b32_e32 v7, 1, v7
	v_ashrrev_i32_e32 v1, 31, v0
	s_addc_u32 s3, s78, s91
	v_exp_f32_e64 v113, -v10
	v_and_b32_e32 v7, 32, v7
	v_add_lshl_u32 v2, s92, v2, 2
	v_lshl_add_u64 v[102:103], v[0:1], 1, s[2:3]
	v_subrev_u32_e32 v102, s34, v102
	v_add_u32_e32 v0, 64, v0
	v_and_b32_e32 v9, 0xc0, v9
	v_and_or_b32 v7, v8, s66, v7
	v_sub_u32_e32 v2, v130, v2
	v_ashrrev_i32_e32 v1, 31, v0
	v_mov_b32_e32 v14, v131
	v_mov_b32_e32 v15, v131
	v_add3_u32 v106, v9, s93, v7
	v_add_u32_e32 v119, 0, v2
	v_lshl_add_u64 v[104:105], v[0:1], 1, s[2:3]
	v_subrev_u32_e32 v104, s34, v104
	v_mov_b32_e32 v0, v131
	v_mov_b32_e32 v1, v131
	v_mov_b32_e32 v2, v131
	v_mov_b32_e32 v3, v131
	v_mov_b32_e32 v4, v131
	v_mov_b32_e32 v5, v131
	v_mov_b32_e32 v6, v131
	v_mov_b32_e32 v7, v131
	v_mov_b32_e32 v8, v131
	v_mov_b32_e32 v9, v131
	v_mov_b32_e32 v10, v131
	v_mov_b32_e32 v11, v131
	v_mov_b32_e32 v12, v131
	v_mov_b32_e32 v13, v131
	v_mov_b64_e32 v[62:63], v[14:15]
	v_mov_b64_e32 v[30:31], v[14:15]
	v_mov_b64_e32 v[46:47], v[14:15]
	s_mov_b32 s0, 1
	s_mov_b32 s62, 0
	s_mov_b32 s1, 2
	s_sub_i32 s53, 0, s47
	s_sub_i32 s6, 0, s52
	v_mov_b32_e32 v120, 0
	s_movk_i32 s7, 0xc300
	s_movk_i32 s22, 0x6000
	v_mov_b32_e32 v196, v107
	v_mov_b32_e32 v197, v108
	v_mov_b32_e32 v198, v109
	v_mov_b32_e32 v199, v110
	v_mov_b64_e32 v[60:61], v[12:13]
	v_mov_b64_e32 v[58:59], v[10:11]
	v_mov_b64_e32 v[56:57], v[8:9]
	v_mov_b64_e32 v[54:55], v[6:7]
	v_mov_b64_e32 v[52:53], v[4:5]
	v_mov_b64_e32 v[50:51], v[2:3]
	v_mov_b64_e32 v[48:49], v[0:1]
	v_mov_b64_e32 v[28:29], v[12:13]
	v_mov_b64_e32 v[26:27], v[10:11]
	v_mov_b64_e32 v[24:25], v[8:9]
	v_mov_b64_e32 v[22:23], v[6:7]
	v_mov_b64_e32 v[20:21], v[4:5]
	v_mov_b64_e32 v[18:19], v[2:3]
	v_mov_b64_e32 v[16:17], v[0:1]
	v_mov_b64_e32 v[44:45], v[12:13]
	v_mov_b64_e32 v[42:43], v[10:11]
	v_mov_b64_e32 v[40:41], v[8:9]
	v_mov_b64_e32 v[38:39], v[6:7]
	v_mov_b64_e32 v[36:37], v[4:5]
	v_mov_b64_e32 v[34:35], v[2:3]
	v_mov_b64_e32 v[32:33], v[0:1]
	s_mov_b32 s49, 1
	s_cmp_lt_u32 s33, 0x100
	s_cbranch_scc1 .Lstg_d1_pre_17
	s_waitcnt vmcnt(3)
	s_barrier

; #define LAS __attribute__((address_space(3)))
; DI void expsum(f32x16& p, float& l_reg, bf16x8& pa0, bf16x8& pa1) {
; #pragma unroll
;     for (int r = 0; r < 16; ++r) p[r] = __builtin_amdgcn_exp2f(p[r]);
;     float ps = 0.f;
; #pragma unroll
;     for (int r = 0; r < 16; ++r) ps += p[r];
;     l_reg += ps; asm volatile("" : "+v"(l_reg));
;     ...
;     ATT_PK4(p, 0, pa0); ATT_PK4(p, 8, pa1);
;     ...
; }
; DI int v_rd_base(int lane) { return ((lane & 3) << 3) | (((lane >> 2) & 3) << 6) | (((lane >> 4) & 1) << 5) | (((lane >> 5) & 1) << 8); }
; template <int OFF> DI s16x4 tr_read(int vb) { s16x4 r; asm volatile("ds_read_b64_tr_b16 %0, %1 offset:%2" : "=&v"(r) : "v"(vb), "i"(OFF) : "memory"); return r; }
; template <int H> DI void v_reads(s16x4* vf, int vb) {
;     vf[0] = tr_read<v_rd_off(0, 2 * H, 0)>(vb); vf[1] = tr_read<v_rd_off(0, 2 * H, 1)>(vb); vf[2] = tr_read<v_rd_off(0, 2 * H + 1, 0)>(vb); vf[3] = tr_read<v_rd_off(0, 2 * H + 1, 1)>(vb);
;     vf[4] = tr_read<v_rd_off(1, 2 * H, 0)>(vb); vf[5] = tr_read<v_rd_off(1, 2 * H, 1)>(vb); vf[6] = tr_read<v_rd_off(1, 2 * H + 1, 0)>(vb); vf[7] = tr_read<v_rd_off(1, 2 * H + 1, 1)>(vb);
;     vf[8] = tr_read<v_rd_off(2, 2 * H, 0)>(vb); vf[9] = tr_read<v_rd_off(2, 2 * H, 1)>(vb); vf[10] = tr_read<v_rd_off(2, 2 * H + 1, 0)>(vb); vf[11] = tr_read<v_rd_off(2, 2 * H + 1, 1)>(vb);
;     vf[12] = tr_read<v_rd_off(3, 2 * H, 0)>(vb); vf[13] = tr_read<v_rd_off(3, 2 * H, 1)>(vb); vf[14] = tr_read<v_rd_off(3, 2 * H + 1, 0)>(vb); vf[15] = tr_read<v_rd_off(3, 2 * H + 1, 1)>(vb);
; }
; DI void pv_mma(f32x16* o, const s16x4* vf, bf16x8 pa0, bf16x8 pa1) {
;     ...
; #pragma unroll
;     for (int d0 = 0; d0 < 4; ++d0) {
;         o[d0] = __builtin_amdgcn_mfma_f32_32x32x16_bf16(pa0, ATT_PK(vf[4 * d0], vf[4 * d0 + 1]), o[d0], 0, 0, 0);
;         o[d0] = __builtin_amdgcn_mfma_f32_32x32x16_bf16(pa1, ATT_PK(vf[4 * d0 + 2], vf[4 * d0 + 3]), o[d0], 0, 0, 0); }
;     ...
; }
; template <int DQK, int D0A, int D0B> DI void k_reads(bf16x8* kf, const LAS unsigned char* Ks, int half, int r32, int hi) {
; #pragma unroll
;     for (int d0 = D0A; d0 < D0B; ++d0) kf[d0 - D0A] = *(const LAS bf16x8*)(Ks + half * (32 * DQK * 2) + kswz<DQK>(r32, (d0 * 16 + hi * 8) * 2));
; }
; template <int D0A, int D0B> DI void qk_mma(f32x16& p, const bf16x8* kf, const bf16x8* qr) {
; #pragma unroll
;     for (int d0 = D0A; d0 < D0B; ++d0) {
.Lstg_d1_top_18:
	s_setprio 0
	s_add_i32 s2, s48, s2
	global_load_lds_dwordx4 v100, s[34:35]
	s_add_i32 s3, s2, 0x400
	s_mov_b32 m0, s2
	s_add_i32 s2, s53, s0
	global_load_lds_dwordx4 v102, s[34:35]
	s_mov_b32 m0, s3
	s_add_i32 s23, s6, s0
	global_load_lds_dwordx4 v104, s[34:35]
	s_cmp_eq_u32 s2, 1
	s_cselect_b64 s[2:3], -1, 0
	s_and_b64 s[74:75], s[4:5], s[2:3]
	s_cmp_eq_u32 s23, 1
	s_cselect_b64 s[2:3], -1, 0
	s_or_b64 s[74:75], s[2:3], s[74:75]
	s_andn2_b64 vcc, exec, s[74:75]
	s_mov_b32 s23, s62
	s_cbranch_vccnz .LBB0_1953
	v_cndmask_b32_e64 v122, v112, v113, s[2:3]
	v_pk_mul_f32 v[14:15], v[14:15], v[122:123] op_sel_hi:[1,0]
	v_pk_mul_f32 v[12:13], v[12:13], v[122:123] op_sel_hi:[1,0]
	v_pk_mul_f32 v[10:11], v[10:11], v[122:123] op_sel_hi:[1,0]
	v_pk_mul_f32 v[8:9], v[8:9], v[122:123] op_sel_hi:[1,0]
	v_pk_mul_f32 v[6:7], v[6:7], v[122:123] op_sel_hi:[1,0]
	v_pk_mul_f32 v[4:5], v[4:5], v[122:123] op_sel_hi:[1,0]
	v_pk_mul_f32 v[2:3], v[2:3], v[122:123] op_sel_hi:[1,0]
	v_pk_mul_f32 v[0:1], v[0:1], v[122:123] op_sel_hi:[1,0]
	v_pk_mul_f32 v[62:63], v[62:63], v[122:123] op_sel_hi:[1,0]
	v_pk_mul_f32 v[60:61], v[60:61], v[122:123] op_sel_hi:[1,0]
	v_pk_mul_f32 v[58:59], v[58:59], v[122:123] op_sel_hi:[1,0]
	v_pk_mul_f32 v[56:57], v[56:57], v[122:123] op_sel_hi:[1,0]
	v_pk_mul_f32 v[54:55], v[54:55], v[122:123] op_sel_hi:[1,0]
	v_pk_mul_f32 v[52:53], v[52:53], v[122:123] op_sel_hi:[1,0]
	v_pk_mul_f32 v[50:51], v[50:51], v[122:123] op_sel_hi:[1,0]
	v_pk_mul_f32 v[48:49], v[48:49], v[122:123] op_sel_hi:[1,0]
	v_pk_mul_f32 v[30:31], v[30:31], v[122:123] op_sel_hi:[1,0]
	v_pk_mul_f32 v[28:29], v[28:29], v[122:123] op_sel_hi:[1,0]
	v_pk_mul_f32 v[26:27], v[26:27], v[122:123] op_sel_hi:[1,0]
	v_pk_mul_f32 v[24:25], v[24:25], v[122:123] op_sel_hi:[1,0]
	v_pk_mul_f32 v[22:23], v[22:23], v[122:123] op_sel_hi:[1,0]
	v_pk_mul_f32 v[20:21], v[20:21], v[122:123] op_sel_hi:[1,0]
	v_pk_mul_f32 v[18:19], v[18:19], v[122:123] op_sel_hi:[1,0]
	v_pk_mul_f32 v[16:17], v[16:17], v[122:123] op_sel_hi:[1,0]
	v_pk_mul_f32 v[46:47], v[46:47], v[122:123] op_sel_hi:[1,0]
	v_pk_mul_f32 v[44:45], v[44:45], v[122:123] op_sel_hi:[1,0]
	v_pk_mul_f32 v[42:43], v[42:43], v[122:123] op_sel_hi:[1,0]
	v_pk_mul_f32 v[40:41], v[40:41], v[122:123] op_sel_hi:[1,0]
	v_pk_mul_f32 v[38:39], v[38:39], v[122:123] op_sel_hi:[1,0]
	v_pk_mul_f32 v[36:37], v[36:37], v[122:123] op_sel_hi:[1,0]
	v_pk_mul_f32 v[34:35], v[34:35], v[122:123] op_sel_hi:[1,0]
	v_pk_mul_f32 v[32:33], v[32:33], v[122:123] op_sel_hi:[1,0]
	v_mul_f32_e32 v120, v120, v122
.LBB0_1953:
	s_add_i32 s3, s0, -1
	ds_read_b128 v[122:125], v196 offset:4096
	ds_read_b128 v[132:135], v197 offset:4096
	s_lshl_b32 s2, s23, 14
	ds_read_b128 v[136:139], v198 offset:4096
	ds_read_b128 v[140:143], v199 offset:4096
	v_add_u32_e32 v121, s2, v106
	ds_read_b64_tr_b16 v[144:145], v121 offset:0
	ds_read_b64_tr_b16 v[146:147], v121 offset:0x800
	ds_read_b64_tr_b16 v[148:149], v121 offset:0x1000
	ds_read_b64_tr_b16 v[150:151], v121 offset:0x1800
	ds_read_b64_tr_b16 v[152:153], v121 offset:0x200
	ds_read_b64_tr_b16 v[154:155], v121 offset:0xa00
	ds_read_b64_tr_b16 v[156:157], v121 offset:0x1200
	ds_read_b64_tr_b16 v[158:159], v121 offset:0x1a00
	ds_read_b64_tr_b16 v[162:163], v121 offset:0x400
	ds_read_b64_tr_b16 v[164:165], v121 offset:0xc00
	ds_read_b64_tr_b16 v[166:167], v121 offset:0x1400
	ds_read_b64_tr_b16 v[168:169], v121 offset:0x1c00
	ds_read_b64_tr_b16 v[170:171], v121 offset:0x600
	ds_read_b64_tr_b16 v[172:173], v121 offset:0xe00
	ds_read_b64_tr_b16 v[174:175], v121 offset:0x1600
	ds_read_b64_tr_b16 v[176:177], v121 offset:0x1e00
	s_setprio 2
	v_exp_f32_e32 v64, v64
	v_exp_f32_e32 v65, v65
	v_exp_f32_e32 v66, v66
	v_exp_f32_e32 v67, v67
	v_exp_f32_e32 v68, v68
	v_exp_f32_e32 v69, v69
	v_add_f32_e32 v126, v65, v64
	v_exp_f32_e32 v70, v70
	v_add_f32_e32 v126, v66, v126
	v_exp_f32_e32 v71, v71
	v_add_f32_e32 v126, v67, v126
	v_exp_f32_e32 v72, v72
	v_add_f32_e32 v126, v68, v126
	v_exp_f32_e32 v73, v73
	v_add_f32_e32 v126, v69, v126
	v_exp_f32_e32 v74, v74
	v_add_f32_e32 v126, v70, v126
	v_exp_f32_e32 v75, v75
	v_add_f32_e32 v126, v71, v126
	v_exp_f32_e32 v76, v76
	v_add_f32_e32 v126, v72, v126
	v_exp_f32_e32 v77, v77
	v_add_f32_e32 v126, v73, v126
	v_exp_f32_e32 v78, v78
	v_add_f32_e32 v126, v74, v126
	v_exp_f32_e32 v79, v79
	v_add_f32_e32 v126, v75, v126
	v_add_f32_e32 v126, v76, v126
	v_add_f32_e32 v126, v77, v126
	v_add_f32_e32 v126, v78, v126
	v_add_f32_e32 v126, v79, v126
	v_add_f32_e32 v120, v126, v120
	v_cvt_pk_bf16_f32 v64, v64, v65
	v_cvt_pk_bf16_f32 v65, v66, v67
	v_cvt_pk_bf16_f32 v66, v68, v69
	v_cvt_pk_bf16_f32 v67, v70, v71
	v_cvt_pk_bf16_f32 v68, v72, v73
	v_cvt_pk_bf16_f32 v69, v74, v75
	v_cvt_pk_bf16_f32 v70, v76, v77
	v_cvt_pk_bf16_f32 v71, v78, v79
	s_nop 0
	v_permlane32_swap_b32_e32 v64, v66
	v_permlane32_swap_b32_e32 v65, v67
	v_permlane32_swap_b32_e32 v68, v70
	v_permlane32_swap_b32_e32 v69, v71
	s_waitcnt lgkmcnt(0)
	s_setprio 1
	v_mfma_f32_32x32x16_bf16 v[0:15], v[64:67], v[144:147], v[0:15]
	s_cmp_lt_i32 s3, s47
	s_cselect_b64 s[74:75], -1, 0
	s_cmp_ge_i32 s3, s52
	s_cselect_b64 s[90:91], -1, 0
	s_or_b64 s[74:75], s[74:75], s[90:91]
	s_and_b64 vcc, exec, s[74:75]
	v_mfma_f32_32x32x16_bf16 v[48:63], v[64:67], v[152:155], v[48:63]
	v_mfma_f32_32x32x16_bf16 v[16:31], v[64:67], v[162:165], v[16:31]
	v_mfma_f32_32x32x16_bf16 v[32:47], v[64:67], v[170:173], v[32:47]
	v_mfma_f32_32x32x16_bf16 v[0:15], v[68:71], v[148:151], v[0:15]
	v_mfma_f32_32x32x16_bf16 v[48:63], v[68:71], v[156:159], v[48:63]
	v_mfma_f32_32x32x16_bf16 v[16:31], v[68:71], v[166:169], v[16:31]
	v_mfma_f32_32x32x16_bf16 v[32:47], v[68:71], v[174:177], v[32:47]
	v_mfma_f32_32x32x16_bf16 v[64:79], v[122:125], v[92:95], 0
	v_mfma_f32_32x32x16_bf16 v[64:79], v[132:135], v[88:91], v[64:79]
	v_mfma_f32_32x32x16_bf16 v[64:79], v[136:139], v[84:87], v[64:79]
	v_mfma_f32_32x32x16_bf16 v[64:79], v[140:143], v[80:83], v[64:79]
	s_setprio 0
	v_add_u32_e32 v122, s7, v119
	s_cbranch_vccnz .LBB0_1955
	v_add_u32_e32 v138, 0x28908, v122
	v_add_u32_e32 v140, 0x28920, v122
	v_add_u32_e32 v142, 0x28928, v122
	v_add_u32_e32 v124, 0x28940, v122
	v_add_u32_e32 v126, 0x28948, v122
	v_add_u32_e32 v132, 0x28960, v122
	v_add_u32_e32 v134, 0x28968, v122
	v_add_u32_e32 v123, 0x28900, v122
	ds_read2_b32 v[124:125], v124 offset1:1
	ds_read2_b32 v[126:127], v126 offset1:1
	ds_read2_b32 v[132:133], v132 offset1:1
	ds_read2_b32 v[134:135], v134 offset1:1
	ds_read2_b32 v[136:137], v123 offset1:1
	ds_read2_b32 v[138:139], v138 offset1:1
	ds_read2_b32 v[140:141], v140 offset1:1
	ds_read2_b32 v[142:143], v142 offset1:1
	s_waitcnt lgkmcnt(0)
	v_pk_add_f32 v[78:79], v[78:79], v[134:135]
	v_pk_add_f32 v[76:77], v[76:77], v[132:133]
	v_pk_add_f32 v[74:75], v[74:75], v[126:127]
	v_pk_add_f32 v[72:73], v[72:73], v[124:125]
	v_pk_add_f32 v[70:71], v[70:71], v[142:143]
	v_pk_add_f32 v[68:69], v[68:69], v[140:141]
	v_pk_add_f32 v[66:67], v[66:67], v[138:139]
	v_pk_add_f32 v[64:65], v[64:65], v[136:137]

; #define SBAR() __builtin_amdgcn_sched_barrier(0)
; #define ATT_DMA_K(t) do { const bf16_t* kg_ = Kh + (size_t)(t) * 64 * LDK; LAS unsigned char* sb_ = lds + ((t) & 3) * KBUF; \
;     _Pragma("unroll") for (int i_ = 0; i_ < NKP; ++i_) __builtin_amdgcn_global_load_lds((const unsigned*)(kg_ + kgo[i_]), (LAS unsigned*)(sb_ + (wid + 8 * i_) * 1024), 16, 0, 0); } while (0)
; #define ATT_DMA_V(t, vs) do { const bf16_t* vg_ = Vh + (size_t)(t) * 64 * LDV; LAS unsigned char* sb_ = lds + V_OFF + (vs) * SHM_V; \
;     _Pragma("unroll") for (int i_ = 0; i_ < 2; ++i_) __builtin_amdgcn_global_load_lds((const unsigned*)(vg_ + vgo[i_]), (LAS unsigned*)(sb_ + (2 * wid + i_) * 1024), 16, 0, 0); } while (0)
; #define ATT_SEG(t) do { if constexpr (MODE != 0) { if (((t) == tL && tL > 0) || (t) == tR) { const float f_ = (t) == tR ? fR : fL; l_reg *= f_; \
;     _Pragma("unroll") for (int d = 0; d < 4; ++d) _Pragma("unroll") for (int r = 0; r < 16; ++r) o[d][r] *= f_; } } } while (0)
; #define ATT_TOP(N) do { asm volatile("s_waitcnt vmcnt(%0)" :: "n"(N) : "memory"); __builtin_amdgcn_s_barrier(); asm volatile("" ::: "memory"); } while (0)
; template <int DQK, int MODE, int LDQ, int LDK, int LDV> ...
;     ...
;     for (int j = 0; j < NT; ++j) {
;         if (j + 2 < NT) ATT_TOP(NKP + 2); else ATT_TOP(0);
;         if (j + 3 < NT) ATT_DMA_K(j + 3);
;         if (j + 2 < NT) ATT_DMA_V(j + 2, v2);
;         ATT_SEG(j); SBAR();
;         ATT_STEP(pA, pB, 0, v0, true, 1, j);
;         ATT_STEP(pB, pA, 1, v0, (j + 1 < NT), 0, j + 1);
;         { const int t_ = v0; v0 = v1; v1 = v2; v2 = t_; }
;     }
.LBB0_1957:
	s_addk_i32 s7, 0x100
	s_addk_i32 s22, 0x2000
	s_add_i32 s0, s0, 1
	v_add_u32_e32 v100, s8, v100
	v_add_u32_e32 v102, s8, v102
	s_cmp_eq_u32 s7, 0
	v_add_u32_e32 v104, s8, v104
	s_cbranch_scc1 .LBB0_1959
	s_mov_b32 s62, s49
	s_mov_b32 s49, s1
	s_mov_b32 s1, s23
	s_branch .LBB0_1951
